# code placement: P1 K-loop head restored to the baseline's byte phase
# speedup vs baseline: 1.0037x; 1.0024x over previous
.LBB0_174:
	s_ashr_i32 s55, s54, 31
	s_lshl_b64 s[6:7], s[54:55], 19
	s_add_u32 s56, s18, s6
	s_addc_u32 s57, s19, s7
	s_and_b64 s[6:7], s[0:1], exec
	s_cselect_b32 s5, s57, s61
	s_cselect_b32 s8, s56, s60
	s_ashr_i32 s49, s48, 31
	s_lshl_b64 s[6:7], s[48:49], 19
	s_add_u32 s58, s52, s6
	s_addc_u32 s59, s53, s7
	s_and_b64 s[6:7], s[0:1], exec
	s_cselect_b32 s30, s59, s65
	s_cselect_b32 s31, s58, s64
	s_add_u32 s60, s60, 0x40080
	s_addc_u32 s61, s61, 0
	s_add_u32 s49, s64, 0x100
	s_addc_u32 s55, s65, 0
	s_mov_b32 s63, -2
	s_nop 0
	s_branch .Lrwp1_first
.LBB0_175:
	ds_read_b128 v[148:151], v159
	ds_read_b128 v[152:155], v159 offset:1024
	ds_read_b128 v[164:167], v159 offset:2048
	ds_read_b128 v[168:171], v159 offset:3072
	ds_read_b128 v[172:175], v160
	ds_read_b128 v[176:179], v160 offset:1024
	ds_read_b128 v[180:183], v160 offset:2048
	ds_read_b128 v[184:187], v160 offset:3072
	v_lshl_add_u64 v[220:221], s[60:61], 0, v[140:141]
	s_add_i32 m0, s72, 0xc000
	ds_read_b128 v[188:191], v161
	ds_read_b128 v[192:195], v161 offset:1024
	ds_read_b128 v[196:199], v161 offset:2048
	ds_read_b128 v[200:203], v161 offset:3072
	ds_read_b128 v[204:207], v161 offset:4096
	ds_read_b128 v[208:211], v161 offset:5120
	ds_read_b128 v[212:215], v161 offset:6144
	ds_read_b128 v[216:219], v161 offset:7168
	global_load_lds_dwordx4 v[220:221], off
	v_lshl_add_u64 v[220:221], s[60:61], 0, v[142:143]
	s_add_i32 m0, s72, 0xe000
	s_nop 0
	global_load_lds_dwordx4 v[220:221], off
	s_add_u32 s6, s60, 0xfffc0080
	s_addc_u32 s7, s61, -1
	s_cmp_eq_u32 s63, 12
	s_cselect_b32 s67, s5, s7
	s_cselect_b32 s66, s8, s6
	s_cselect_b32 s65, s30, s55
	s_cselect_b32 s64, s31, s49
	s_waitcnt vmcnt(8)
	s_waitcnt lgkmcnt(0)
	s_barrier
	s_setprio 1
	s_waitcnt lgkmcnt(0)
	v_mfma_f32_16x16x32_bf16 v[126:129], v[148:151], v[188:191], v[126:129]
	v_mfma_f32_16x16x32_bf16 v[122:125], v[164:167], v[188:191], v[122:125]
	v_mfma_f32_16x16x32_bf16 v[110:113], v[148:151], v[196:199], v[110:113]
	v_mfma_f32_16x16x32_bf16 v[106:109], v[164:167], v[196:199], v[106:109]
	v_mfma_f32_16x16x32_bf16 v[94:97], v[148:151], v[204:207], v[94:97]
	v_mfma_f32_16x16x32_bf16 v[90:93], v[164:167], v[204:207], v[90:93]
	v_mfma_f32_16x16x32_bf16 v[78:81], v[148:151], v[212:215], v[78:81]
	v_mfma_f32_16x16x32_bf16 v[74:77], v[164:167], v[212:215], v[74:77]
	v_mfma_f32_16x16x32_bf16 v[126:129], v[152:155], v[192:195], v[126:129]
	v_mfma_f32_16x16x32_bf16 v[122:125], v[168:171], v[192:195], v[122:125]
	v_mfma_f32_16x16x32_bf16 v[110:113], v[152:155], v[200:203], v[110:113]
	v_mfma_f32_16x16x32_bf16 v[106:109], v[168:171], v[200:203], v[106:109]
	v_mfma_f32_16x16x32_bf16 v[94:97], v[152:155], v[208:211], v[94:97]
	v_mfma_f32_16x16x32_bf16 v[90:93], v[168:171], v[208:211], v[90:93]
	v_mfma_f32_16x16x32_bf16 v[78:81], v[152:155], v[216:219], v[78:81]
	v_mfma_f32_16x16x32_bf16 v[74:77], v[168:171], v[216:219], v[74:77]
	s_setprio 0
	s_setprio 1
	v_mfma_f32_16x16x32_bf16 v[118:121], v[172:175], v[188:191], v[118:121]
	v_mfma_f32_16x16x32_bf16 v[114:117], v[180:183], v[188:191], v[114:117]
	v_mfma_f32_16x16x32_bf16 v[102:105], v[172:175], v[196:199], v[102:105]
	v_mfma_f32_16x16x32_bf16 v[98:101], v[180:183], v[196:199], v[98:101]
	v_mfma_f32_16x16x32_bf16 v[86:89], v[172:175], v[204:207], v[86:89]
	v_mfma_f32_16x16x32_bf16 v[82:85], v[180:183], v[204:207], v[82:85]
	v_mfma_f32_16x16x32_bf16 v[70:73], v[172:175], v[212:215], v[70:73]
	v_mfma_f32_16x16x32_bf16 v[66:69], v[180:183], v[212:215], v[66:69]
	v_mfma_f32_16x16x32_bf16 v[118:121], v[176:179], v[192:195], v[118:121]
	v_mfma_f32_16x16x32_bf16 v[114:117], v[184:187], v[192:195], v[114:117]
	v_mfma_f32_16x16x32_bf16 v[102:105], v[176:179], v[200:203], v[102:105]
	v_mfma_f32_16x16x32_bf16 v[98:101], v[184:187], v[200:203], v[98:101]
	v_mfma_f32_16x16x32_bf16 v[86:89], v[176:179], v[208:211], v[86:89]
	v_mfma_f32_16x16x32_bf16 v[82:85], v[184:187], v[208:211], v[82:85]
	v_mfma_f32_16x16x32_bf16 v[70:73], v[176:179], v[216:219], v[70:73]
	v_mfma_f32_16x16x32_bf16 v[66:69], v[184:187], v[216:219], v[66:69]
	s_setprio 0
	s_barrier
	s_add_i32 s6, s85, s47
	v_lshl_add_u64 v[220:221], s[64:65], 0, v[132:133]
	s_mov_b32 m0, s6
	ds_read_b128 v[188:191], v161 offset:16384
	ds_read_b128 v[192:195], v161 offset:17408
	ds_read_b128 v[196:199], v161 offset:18432
	ds_read_b128 v[200:203], v161 offset:19456
	ds_read_b128 v[204:207], v161 offset:20480
	ds_read_b128 v[208:211], v161 offset:21504
	ds_read_b128 v[212:215], v161 offset:22528
	ds_read_b128 v[216:219], v161 offset:23552
	global_load_lds_dwordx4 v[220:221], off
	s_add_i32 m0, s6, 0x2000
	s_add_u32 s6, s64, 0x40000
	v_lshl_add_u64 v[222:223], s[64:65], 0, v[136:137]
	s_addc_u32 s7, s65, 0
	s_add_i32 s88, s86, s47
	global_load_lds_dwordx4 v[222:223], off
	v_lshl_add_u64 v[224:225], s[6:7], 0, v[132:133]
	s_mov_b32 m0, s88
	v_lshl_add_u64 v[226:227], s[66:67], 0, v[134:135]
	global_load_lds_dwordx4 v[224:225], off
	v_lshl_add_u64 v[224:225], s[6:7], 0, v[136:137]
	s_add_i32 m0, s88, 0x2000
	s_nop 0
	global_load_lds_dwordx4 v[224:225], off
	v_lshl_add_u64 v[224:225], s[66:67], 0, v[130:131]
	s_mov_b32 m0, s72
	s_nop 0
	global_load_lds_dwordx4 v[224:225], off
	s_mov_b32 m0, s73
	s_nop 0
	global_load_lds_dwordx4 v[226:227], off
	s_waitcnt vmcnt(8)
	s_waitcnt lgkmcnt(0)
	s_barrier
	s_setprio 1
	s_waitcnt lgkmcnt(0)
	v_mfma_f32_16x16x32_bf16 v[62:65], v[148:151], v[188:191], v[62:65]
	v_mfma_f32_16x16x32_bf16 v[58:61], v[164:167], v[188:191], v[58:61]
	v_mfma_f32_16x16x32_bf16 v[46:49], v[148:151], v[196:199], v[46:49]
	v_mfma_f32_16x16x32_bf16 v[42:45], v[164:167], v[196:199], v[42:45]
	v_mfma_f32_16x16x32_bf16 v[30:33], v[148:151], v[204:207], v[30:33]
	v_mfma_f32_16x16x32_bf16 v[26:29], v[164:167], v[204:207], v[26:29]
	v_mfma_f32_16x16x32_bf16 v[14:17], v[148:151], v[212:215], v[14:17]
	v_mfma_f32_16x16x32_bf16 v[10:13], v[164:167], v[212:215], v[10:13]
	v_mfma_f32_16x16x32_bf16 v[62:65], v[152:155], v[192:195], v[62:65]
	v_mfma_f32_16x16x32_bf16 v[58:61], v[168:171], v[192:195], v[58:61]
	v_mfma_f32_16x16x32_bf16 v[46:49], v[152:155], v[200:203], v[46:49]
	v_mfma_f32_16x16x32_bf16 v[42:45], v[168:171], v[200:203], v[42:45]
	v_mfma_f32_16x16x32_bf16 v[30:33], v[152:155], v[208:211], v[30:33]
	v_mfma_f32_16x16x32_bf16 v[26:29], v[168:171], v[208:211], v[26:29]
	v_mfma_f32_16x16x32_bf16 v[14:17], v[152:155], v[216:219], v[14:17]
	v_mfma_f32_16x16x32_bf16 v[10:13], v[168:171], v[216:219], v[10:13]
	s_setprio 0
	s_setprio 1
	v_mfma_f32_16x16x32_bf16 v[54:57], v[172:175], v[188:191], v[54:57]
	v_mfma_f32_16x16x32_bf16 v[50:53], v[180:183], v[188:191], v[50:53]
	v_mfma_f32_16x16x32_bf16 v[38:41], v[172:175], v[196:199], v[38:41]
	v_mfma_f32_16x16x32_bf16 v[34:37], v[180:183], v[196:199], v[34:37]
	v_mfma_f32_16x16x32_bf16 v[22:25], v[172:175], v[204:207], v[22:25]
	v_mfma_f32_16x16x32_bf16 v[18:21], v[180:183], v[204:207], v[18:21]
	v_mfma_f32_16x16x32_bf16 v[6:9], v[172:175], v[212:215], v[6:9]
	v_mfma_f32_16x16x32_bf16 v[2:5], v[180:183], v[212:215], v[2:5]
	v_mfma_f32_16x16x32_bf16 v[54:57], v[176:179], v[192:195], v[54:57]
	v_mfma_f32_16x16x32_bf16 v[50:53], v[184:187], v[192:195], v[50:53]
	v_mfma_f32_16x16x32_bf16 v[38:41], v[176:179], v[200:203], v[38:41]
	v_mfma_f32_16x16x32_bf16 v[34:37], v[184:187], v[200:203], v[34:37]
	v_mfma_f32_16x16x32_bf16 v[22:25], v[176:179], v[208:211], v[22:25]
	v_mfma_f32_16x16x32_bf16 v[18:21], v[184:187], v[208:211], v[18:21]
	v_mfma_f32_16x16x32_bf16 v[6:9], v[176:179], v[216:219], v[6:9]
	v_mfma_f32_16x16x32_bf16 v[2:5], v[184:187], v[216:219], v[2:5]
	s_setprio 0
	s_barrier
	s_add_i32 s88, 0, 0x18000
	v_add_u32_e32 v138, s88, v158
	s_add_i32 s89, 0, 0x1c000
	ds_read_b128 v[148:151], v138
	ds_read_b128 v[152:155], v138 offset:1024
	ds_read_b128 v[164:167], v138 offset:2048
	ds_read_b128 v[168:171], v138 offset:3072
	v_add_u32_e32 v138, s89, v158
	ds_read_b128 v[172:175], v138
	ds_read_b128 v[176:179], v138 offset:1024
	ds_read_b128 v[180:183], v138 offset:2048
	ds_read_b128 v[184:187], v138 offset:3072
	s_add_u32 s6, s66, 0x40000
	s_addc_u32 s7, s67, 0
	s_mov_b32 m0, s74
	v_lshl_add_u64 v[228:229], s[6:7], 0, v[130:131]
	ds_read_b128 v[188:191], v161 offset:32768
	ds_read_b128 v[192:195], v161 offset:33792
	ds_read_b128 v[196:199], v161 offset:34816
	ds_read_b128 v[200:203], v161 offset:35840
	ds_read_b128 v[204:207], v161 offset:36864
	ds_read_b128 v[208:211], v161 offset:37888
	ds_read_b128 v[212:215], v161 offset:38912
	ds_read_b128 v[216:219], v161 offset:39936
	global_load_lds_dwordx4 v[228:229], off
	v_lshl_add_u64 v[228:229], s[6:7], 0, v[134:135]
	s_mov_b32 m0, s75
	s_nop 0
	global_load_lds_dwordx4 v[228:229], off
	s_waitcnt vmcnt(8)
	s_waitcnt lgkmcnt(0)
	s_barrier
	s_setprio 1
	s_waitcnt lgkmcnt(0)
	v_mfma_f32_16x16x32_bf16 v[126:129], v[148:151], v[188:191], v[126:129]
	v_mfma_f32_16x16x32_bf16 v[122:125], v[164:167], v[188:191], v[122:125]
	v_mfma_f32_16x16x32_bf16 v[110:113], v[148:151], v[196:199], v[110:113]
	v_mfma_f32_16x16x32_bf16 v[106:109], v[164:167], v[196:199], v[106:109]
	v_mfma_f32_16x16x32_bf16 v[94:97], v[148:151], v[204:207], v[94:97]
	v_mfma_f32_16x16x32_bf16 v[90:93], v[164:167], v[204:207], v[90:93]
	v_mfma_f32_16x16x32_bf16 v[78:81], v[148:151], v[212:215], v[78:81]
	v_mfma_f32_16x16x32_bf16 v[74:77], v[164:167], v[212:215], v[74:77]
	v_mfma_f32_16x16x32_bf16 v[126:129], v[152:155], v[192:195], v[126:129]
	v_mfma_f32_16x16x32_bf16 v[122:125], v[168:171], v[192:195], v[122:125]
	v_mfma_f32_16x16x32_bf16 v[110:113], v[152:155], v[200:203], v[110:113]
	v_mfma_f32_16x16x32_bf16 v[106:109], v[168:171], v[200:203], v[106:109]
	v_mfma_f32_16x16x32_bf16 v[94:97], v[152:155], v[208:211], v[94:97]
	v_mfma_f32_16x16x32_bf16 v[90:93], v[168:171], v[208:211], v[90:93]
	v_mfma_f32_16x16x32_bf16 v[78:81], v[152:155], v[216:219], v[78:81]
	v_mfma_f32_16x16x32_bf16 v[74:77], v[168:171], v[216:219], v[74:77]
	s_setprio 0
	s_setprio 1
	v_mfma_f32_16x16x32_bf16 v[118:121], v[172:175], v[188:191], v[118:121]
	v_mfma_f32_16x16x32_bf16 v[114:117], v[180:183], v[188:191], v[114:117]
	v_mfma_f32_16x16x32_bf16 v[102:105], v[172:175], v[196:199], v[102:105]
	v_mfma_f32_16x16x32_bf16 v[98:101], v[180:183], v[196:199], v[98:101]
	v_mfma_f32_16x16x32_bf16 v[86:89], v[172:175], v[204:207], v[86:89]
	v_mfma_f32_16x16x32_bf16 v[82:85], v[180:183], v[204:207], v[82:85]
	v_mfma_f32_16x16x32_bf16 v[70:73], v[172:175], v[212:215], v[70:73]
	v_mfma_f32_16x16x32_bf16 v[66:69], v[180:183], v[212:215], v[66:69]
	v_mfma_f32_16x16x32_bf16 v[118:121], v[176:179], v[192:195], v[118:121]
	v_mfma_f32_16x16x32_bf16 v[114:117], v[184:187], v[192:195], v[114:117]
	v_mfma_f32_16x16x32_bf16 v[102:105], v[176:179], v[200:203], v[102:105]
	v_mfma_f32_16x16x32_bf16 v[98:101], v[184:187], v[200:203], v[98:101]
	v_mfma_f32_16x16x32_bf16 v[86:89], v[176:179], v[208:211], v[86:89]
	v_mfma_f32_16x16x32_bf16 v[82:85], v[184:187], v[208:211], v[82:85]
	v_mfma_f32_16x16x32_bf16 v[70:73], v[176:179], v[216:219], v[70:73]
	v_mfma_f32_16x16x32_bf16 v[66:69], v[184:187], v[216:219], v[66:69]
	s_setprio 0
	s_barrier
	s_add_i32 s6, s88, s47
	v_lshl_add_u64 v[220:221], v[220:221], 0, s[20:21]
	s_mov_b32 m0, s6
	ds_read_b128 v[188:191], v161 offset:49152
	ds_read_b128 v[192:195], v161 offset:50176
	ds_read_b128 v[196:199], v161 offset:51200
	ds_read_b128 v[200:203], v161 offset:52224
	ds_read_b128 v[204:207], v161 offset:53248
	ds_read_b128 v[208:211], v161 offset:54272
	ds_read_b128 v[212:215], v161 offset:55296
	ds_read_b128 v[216:219], v161 offset:56320
	global_load_lds_dwordx4 v[220:221], off
	s_add_i32 m0, s6, 0x2000
	s_add_u32 s6, s64, 0x40080
	v_lshl_add_u64 v[220:221], v[222:223], 0, s[20:21]
	s_addc_u32 s7, s65, 0
	s_add_i32 s64, s89, s47
	global_load_lds_dwordx4 v[220:221], off
	v_lshl_add_u64 v[220:221], s[6:7], 0, v[132:133]
	s_mov_b32 m0, s64
	s_nop 0
	global_load_lds_dwordx4 v[220:221], off
	v_lshl_add_u64 v[220:221], s[6:7], 0, v[136:137]
	s_add_i32 m0, s64, 0x2000
	s_nop 0
	global_load_lds_dwordx4 v[220:221], off
	v_lshl_add_u64 v[220:221], v[224:225], 0, s[20:21]
	s_mov_b32 m0, s77
	s_nop 0
	global_load_lds_dwordx4 v[220:221], off
	v_lshl_add_u64 v[220:221], v[226:227], 0, s[20:21]
	s_mov_b32 m0, s78
	s_nop 0
	global_load_lds_dwordx4 v[220:221], off
	s_waitcnt vmcnt(8)
	s_waitcnt lgkmcnt(0)
	s_barrier
	s_setprio 1
	s_waitcnt lgkmcnt(0)
	v_mfma_f32_16x16x32_bf16 v[62:65], v[148:151], v[188:191], v[62:65]
	v_mfma_f32_16x16x32_bf16 v[58:61], v[164:167], v[188:191], v[58:61]
	v_mfma_f32_16x16x32_bf16 v[46:49], v[148:151], v[196:199], v[46:49]
	v_mfma_f32_16x16x32_bf16 v[42:45], v[164:167], v[196:199], v[42:45]
	v_mfma_f32_16x16x32_bf16 v[30:33], v[148:151], v[204:207], v[30:33]
	v_mfma_f32_16x16x32_bf16 v[26:29], v[164:167], v[204:207], v[26:29]
	v_mfma_f32_16x16x32_bf16 v[14:17], v[148:151], v[212:215], v[14:17]
	v_mfma_f32_16x16x32_bf16 v[10:13], v[164:167], v[212:215], v[10:13]
	v_mfma_f32_16x16x32_bf16 v[62:65], v[152:155], v[192:195], v[62:65]
	v_mfma_f32_16x16x32_bf16 v[58:61], v[168:171], v[192:195], v[58:61]
	v_mfma_f32_16x16x32_bf16 v[46:49], v[152:155], v[200:203], v[46:49]
	v_mfma_f32_16x16x32_bf16 v[42:45], v[168:171], v[200:203], v[42:45]
	v_mfma_f32_16x16x32_bf16 v[30:33], v[152:155], v[208:211], v[30:33]
	v_mfma_f32_16x16x32_bf16 v[26:29], v[168:171], v[208:211], v[26:29]
	v_mfma_f32_16x16x32_bf16 v[14:17], v[152:155], v[216:219], v[14:17]
	v_mfma_f32_16x16x32_bf16 v[10:13], v[168:171], v[216:219], v[10:13]
	s_setprio 0
	s_setprio 1
	v_mfma_f32_16x16x32_bf16 v[54:57], v[172:175], v[188:191], v[54:57]
	v_mfma_f32_16x16x32_bf16 v[50:53], v[180:183], v[188:191], v[50:53]
	v_mfma_f32_16x16x32_bf16 v[38:41], v[172:175], v[196:199], v[38:41]
	v_mfma_f32_16x16x32_bf16 v[34:37], v[180:183], v[196:199], v[34:37]
	v_mfma_f32_16x16x32_bf16 v[22:25], v[172:175], v[204:207], v[22:25]
	v_mfma_f32_16x16x32_bf16 v[18:21], v[180:183], v[204:207], v[18:21]
	v_mfma_f32_16x16x32_bf16 v[6:9], v[172:175], v[212:215], v[6:9]
	v_mfma_f32_16x16x32_bf16 v[2:5], v[180:183], v[212:215], v[2:5]
	v_mfma_f32_16x16x32_bf16 v[54:57], v[176:179], v[192:195], v[54:57]
	v_mfma_f32_16x16x32_bf16 v[50:53], v[184:187], v[192:195], v[50:53]
	v_mfma_f32_16x16x32_bf16 v[38:41], v[176:179], v[200:203], v[38:41]
	v_mfma_f32_16x16x32_bf16 v[34:37], v[184:187], v[200:203], v[34:37]
	v_mfma_f32_16x16x32_bf16 v[22:25], v[176:179], v[208:211], v[22:25]
	v_mfma_f32_16x16x32_bf16 v[18:21], v[184:187], v[208:211], v[18:21]
	v_mfma_f32_16x16x32_bf16 v[6:9], v[176:179], v[216:219], v[6:9]
	v_mfma_f32_16x16x32_bf16 v[2:5], v[184:187], v[216:219], v[2:5]
	s_setprio 0
	s_add_i32 s63, s63, 2
	s_add_u32 s60, s60, 0x100
	s_addc_u32 s61, s61, 0
	s_add_u32 s49, s49, 0x100
	s_addc_u32 s55, s55, 0
	s_cmp_gt_u32 s63, 13
	s_barrier
	s_cbranch_scc0 .LBB0_175
	s_nop 0
